# c28: SSD pass-3 staging pieces reassigned so each of a thread's five pieces has one fixed destination (x / B / C): straight-line staging instead of three lane-masked paths per piece
# speedup vs baseline: 1.0238x; 1.0238x over previous
; template <int PASS>
; __device__ void ssd_item(const Params& p, int item, int l, unsigned char* smem) {
;     ...
;     const unsigned char* xb_ = (const unsigned char*)((const bf16_t*)(p.ws + WS_XBCC) + tokb * 1024);
;     unsigned soff[5];
; #pragma unroll
;     for (int i = 0; i < 5; ++i) { const int u = tid + 256 * i, lrow = u / 40, ci = u % 40;
;         const int scol = ci < 8 ? h * 64 + ci * 8 : (ci < 24 ? 512 + grp * 128 + (ci * 8 - 64) : 768 + grp * 128 + (ci * 8 - 192));
;         soff[i] = (unsigned)((lrow * 1024 + scol) * 2); }
;     for (int si = 0; si < NSUB; ++si) {
;         const int scn = dir ? (NSUB - 1 - si) : si;
;         const int t0 = seg * SEGLEN + scn * TSUB;
;         __syncthreads();
;         u32x4 raw[5];
; #pragma unroll
;         for (int i = 0; i < 5; ++i) raw[i] = *(const u32x4*)(xb_ + ((unsigned)(t0 * 2048) + soff[i]));
.LBB0_910:
	s_andn2_saveexec_b64 s[50:51], s[50:51]
	v_add_u32_e32 v47, s21, v45
	s_or_b64 exec, exec, s[50:51]
	v_lshlrev_b32_e32 v49, 11, v65
	s_lshl_b64 s[22:23], s[48:49], 24
	v_lshl_add_u32 v67, v46, 1, v49
	v_lshlrev_b32_e32 v46, 11, v64
	s_and_b64 s[24:25], exec, s[36:37]
	s_mov_b32 s20, 0x15800000
	v_lshl_add_u32 v68, v43, 1, v46
	v_lshlrev_b32_e32 v43, 11, v63
	s_cselect_b32 s24, s20, 0x16800000
	v_lshl_add_u32 v69, v41, 1, v43
	v_lshlrev_b32_e32 v41, 11, v62
	s_add_u32 s24, s92, s24
	v_lshl_add_u32 v70, v39, 1, v41
	s_addc_u32 s25, s93, 0
	v_lshlrev_b32_e32 v39, 11, v66
	v_lshlrev_b32_e32 v43, 4, v35
	v_lshlrev_b32_e32 v48, 2, v35
	v_lshl_add_u32 v71, v47, 1, v39
	s_add_u32 s96, s17, s22
	v_and_b32_e32 v39, 16, v34
	v_add_u32_e32 v56, v52, v43
	v_and_or_b32 v73, v33, -16, v53
	s_addc_u32 s97, s18, s23
	v_mad_u64_u32 v[58:59], s[22:23], v73, s0, v[56:57]
	v_mad_u64_u32 v[46:47], s[22:23], v73, s1, v[52:53]
	v_lshlrev_b32_e32 v33, 1, v39
	v_lshlrev_b32_e32 v80, 1, v48
	v_lshlrev_b32_e32 v32, 2, v32
	s_lshl_b32 s21, s21, 1
	v_add3_u32 v74, v46, v33, v80
	v_lshrrev_b32_e32 v33, 2, v53
	v_and_b32_e32 v46, 12, v32
	s_add_u32 s22, s24, s21
	v_or_b32_e32 v41, v39, v53
	v_or_b32_e32 v59, v39, v48
	v_lshl_or_b32 v39, v35, 3, v33
	v_or_b32_e32 v32, v34, v46
	s_addc_u32 s23, s25, 0
	v_ashrrev_i32_e32 v35, 31, v34
	v_lshlrev_b32_e32 v47, 1, v32
	v_lshl_add_u64 v[32:33], v[34:35], 1, s[22:23]
	v_lshl_add_u64 v[60:61], v[32:33], 0, v[80:81]
	v_lshlrev_b32_e32 v32, 1, v34
	v_mul_lo_u32 v34, v62, s0
	v_lshlrev_b32_e32 v35, 4, v37
	v_add3_u32 v77, v52, v34, v35
	v_lshlrev_b32_e32 v34, 7, v62
	v_sub_u32_e32 v79, v77, v34
	v_mul_lo_u32 v34, v63, s0
	v_lshlrev_b32_e32 v35, 4, v38
	v_add3_u32 v76, v52, v32, v80
	v_add3_u32 v80, v52, v34, v35
	v_lshlrev_b32_e32 v34, 7, v63
	v_sub_u32_e32 v83, v80, v34
	v_mul_lo_u32 v34, v64, s0
	v_lshlrev_b32_e32 v35, 4, v40
	v_add3_u32 v84, v52, v34, v35
	v_lshlrev_b32_e32 v34, 7, v64
	v_sub_u32_e32 v86, v84, v34
	v_mul_lo_u32 v34, v65, s0
	v_lshlrev_b32_e32 v35, 4, v42
	v_add3_u32 v87, v52, v34, v35
	v_lshlrev_b32_e32 v34, 7, v65
	v_sub_u32_e32 v89, v87, v34
	v_mul_lo_u32 v34, v66, s0
	v_lshlrev_b32_e32 v35, 1, v45
	v_add3_u32 v90, v52, v34, v35
	v_lshlrev_b32_e32 v34, 7, v66
	v_cmp_le_i32_e32 vcc, v59, v73
	v_sub_u32_e32 v92, v90, v34
	v_mad_u32_u24 v72, v41, s0, v56
	v_cndmask_b32_e64 v34, 0, 1, vcc
	v_cmp_ge_i32_e32 vcc, v59, v73
	v_mad_u32_u24 v41, v39, s3, v52
	v_mad_u32_u24 v32, v39, s0, v52
	v_cndmask_b32_e64 v35, 0, 1, vcc
	v_cndmask_b32_e64 v34, v35, v34, s[36:37]
	v_and_b32_e32 v34, 1, v34
	v_cmp_eq_u32_e64 s[58:59], 1, v34
	v_or_b32_e32 v34, 1, v59
	v_cmp_lt_i32_e32 vcc, v59, v73
	v_lshlrev_b32_e32 v33, 1, v46
	s_mov_b32 s20, 0
	v_cndmask_b32_e64 v35, 0, 1, vcc
	v_cmp_ge_i32_e32 vcc, v34, v73
	v_add_u32_e32 v75, v36, v43
	v_cmp_lt_u32_e64 s[48:49], 23, v37
	v_cndmask_b32_e64 v34, 0, 1, vcc
	v_cndmask_b32_e64 v34, v34, v35, s[36:37]
	v_and_b32_e32 v34, 1, v34
	v_cmp_eq_u32_e64 s[60:61], 1, v34
	v_or_b32_e32 v34, 2, v59
	v_cmp_le_i32_e32 vcc, v34, v73
	v_add_u32_e32 v78, 0xffffff80, v77
	v_cmp_lt_u32_e64 s[50:51], 23, v38
	v_cndmask_b32_e64 v35, 0, 1, vcc
	v_cmp_ge_i32_e32 vcc, v34, v73
	v_add_u32_e32 v82, 0xffffff80, v80
	v_cmp_lt_u32_e64 s[52:53], 23, v40
	v_cndmask_b32_e64 v34, 0, 1, vcc
	v_cndmask_b32_e64 v34, v34, v35, s[36:37]
	v_and_b32_e32 v34, 1, v34
	v_cmp_eq_u32_e64 s[62:63], 1, v34
	v_or_b32_e32 v34, 3, v59
	v_cmp_le_i32_e32 vcc, v34, v73
	v_add_u32_e32 v85, 0xffffff80, v84
	v_cmp_lt_u32_e64 s[54:55], 23, v42
	v_cndmask_b32_e64 v35, 0, 1, vcc
	v_cmp_ge_i32_e32 vcc, v34, v73
	v_add_u32_e32 v88, 0xffffff80, v87
	v_cmp_lt_u32_e64 s[56:57], 23, v44
	v_cndmask_b32_e64 v34, 0, 1, vcc
	v_cndmask_b32_e64 v34, v34, v35, s[36:37]
	v_and_b32_e32 v34, 1, v34
	v_add_u32_e32 v91, 0xffffff80, v90
	v_cmp_eq_u32_e64 s[64:65], 1, v34
	v_mov_b32_e32 v55, v54
	v_add_u32_e32 v93, v32, v33
	v_add_u32_e32 v94, v41, v47
	s_and_b64 s[22:23], exec, s[36:37]
	s_cselect_b32 s99, 0, 15
	s_cselect_b32 s100, 1, 14
	s_lshl_b32 s99, s99, 5
	s_add_i32 s99, s99, s12
	s_lshl_b32 s99, s99, 11
	s_lshl_b32 s100, s100, 5
	s_add_i32 s100, s100, s12
	s_lshl_b32 s100, s100, 11
	s_bfe_u32 s22, s19, 0x30004
	s_lshr_b32 s23, s22, 2
	s_lshl_b32 s22, s22, 7
	s_lshl_b32 s23, s23, 8
	s_addk_i32 s23, 0x400
	v_and_b32_e32 v140, 0xff, v210
	v_lshrrev_b32_e32 v66, 3, v140
	v_and_b32_e32 v141, 7, v140
	v_lshlrev_b32_e32 v70, 11, v66
	v_lshl_add_u32 v70, v141, 4, v70
	v_add_u32_e32 v70, s22, v70
	v_mul_u32_u24_e32 v209, 0x90, v66
	v_lshl_add_u32 v209, v141, 4, v209
	v_add_u32_e32 v209, v52, v209
	v_lshrrev_b32_e32 v141, 4, v140
	v_and_b32_e32 v140, 15, v140
	v_lshlrev_b32_e32 v69, 11, v141
	v_lshl_add_u32 v69, v140, 4, v69
	v_add_u32_e32 v69, s23, v69
	v_add_u32_e32 v68, 0x8000, v69
	v_add_u32_e32 v67, 0x200, v69
	v_add_u32_e32 v71, 0x8000, v67
	v_mul_u32_u24_e32 v208, 0x110, v141
	v_lshl_add_u32 v208, v140, 4, v208
	v_add_u32_e32 v208, v52, v208
	v_add_u32_e32 v140, s99, v70
	global_load_dwordx4 v[120:123], v140, s[96:97]
	v_add_u32_e32 v141, s99, v69
	global_load_dwordx4 v[124:127], v141, s[96:97]
	v_add_u32_e32 v140, s99, v68
	global_load_dwordx4 v[128:131], v140, s[96:97]
	v_add_u32_e32 v141, s99, v67
	global_load_dwordx4 v[132:135], v141, s[96:97]
	v_add_u32_e32 v140, s99, v71
	global_load_dwordx4 v[136:139], v140, s[96:97]
	v_add_u32_e32 v140, s100, v70
	global_load_dwordx4 v[142:145], v140, s[96:97]
	v_add_u32_e32 v141, s100, v69
	global_load_dwordx4 v[146:149], v141, s[96:97]
	v_add_u32_e32 v140, s100, v68
	global_load_dwordx4 v[150:153], v140, s[96:97]
	v_add_u32_e32 v141, s100, v67
	global_load_dwordx4 v[154:157], v141, s[96:97]
	v_add_u32_e32 v140, s100, v71
	global_load_dwordx4 v[158:161], v140, s[96:97]
	s_branch .LBB0_914

; __device__ __forceinline__ unsigned pk2(float lo, float hi) { f32x2 v = {lo, hi}; bf16x2_t b = __builtin_convertvector(v, bf16x2_t); return __builtin_bit_cast(unsigned, b); }
; __device__ __forceinline__ float bflo(unsigned u) { return __uint_as_float(u << 16); }
; __device__ __forceinline__ float bfhi(unsigned u) { return __uint_as_float(u & 0xffff0000u); }
; template <int PASS>
; __device__ void ssd_item(const Params& p, int item, int l, unsigned char* smem) {
;     ...
;         const float* s_dt = s_dta + scn * TSUB; const float* s_c = s_cA + scn * TSUB; const float* s_rs = s_rsA + scn * TSUB; const float* s_wl = s_wlA + scn * TSUB;
;         const float stot = s_totA[scn];
;         segtot += stot;
; #pragma unroll
;         for (int i = 0; i < 5; ++i) { const int u = tid + 256 * i, lrow = u / 40, ci = u % 40, lc = ci * 8; const u32x4 o = raw[i];
;             if (ci < 8) { *(u32x4*)(Xs + lrow * 72 + lc) = o; const float wl = s_wl[lrow];
;                 u32x4 o2; o2.x = pk2(bflo(o.x) * wl, bfhi(o.x) * wl); o2.y = pk2(bflo(o.y) * wl, bfhi(o.y) * wl); o2.z = pk2(bflo(o.z) * wl, bfhi(o.z) * wl); o2.w = pk2(bflo(o.w) * wl, bfhi(o.w) * wl);
;                 *(u32x4*)(Xws + lrow * 72 + lc) = o2; }
;             else if (ci < 24) *(u32x4*)(Bs + lrow * 136 + (lc - 64)) = o;
;             else *(u32x4*)(Cs + lrow * 136 + (lc - 192)) = o; }
.Lssd3_join:
	v_lshl_add_u32 v96, s22, 7, v52
	s_mul_i32 s23, s22, 0xffffff84
	v_add_u32_e32 v97, s23, v96
	ds_read_b32 v95, v97 offset:54272
	v_lshl_add_u32 v164, v66, 2, v96
	ds_read_b32 v164, v164 offset:50688
	ds_write_b128 v208, v[44:47]
	ds_write_b128 v208, v[40:43] offset:4352
	ds_write_b128 v208, v[36:39] offset:8704
	ds_write_b128 v208, v[32:35] offset:13056
	ds_write_b128 v209, v[48:51] offset:17408
	s_waitcnt lgkmcnt(5)
	v_lshlrev_b32_e32 v140, 16, v48
	v_and_b32_e32 v141, 0xffff0000, v48
	v_pk_mul_f32 v[140:141], v[164:165], v[140:141] op_sel_hi:[0,1]
	v_cvt_pk_bf16_f32 v48, v140, v141
	v_lshlrev_b32_e32 v140, 16, v49
	v_and_b32_e32 v141, 0xffff0000, v49
	v_pk_mul_f32 v[140:141], v[164:165], v[140:141] op_sel_hi:[0,1]
	v_cvt_pk_bf16_f32 v49, v140, v141
	v_lshlrev_b32_e32 v140, 16, v50
	v_and_b32_e32 v141, 0xffff0000, v50
	v_pk_mul_f32 v[140:141], v[164:165], v[140:141] op_sel_hi:[0,1]
	v_cvt_pk_bf16_f32 v50, v140, v141
	v_lshlrev_b32_e32 v140, 16, v51
	v_and_b32_e32 v141, 0xffff0000, v51
	v_pk_mul_f32 v[140:141], v[164:165], v[140:141] op_sel_hi:[0,1]
	v_cvt_pk_bf16_f32 v51, v140, v141
	ds_write_b128 v209, v[48:51] offset:22016

; __device__ __forceinline__ float bflo(unsigned u) { return __uint_as_float(u << 16); }
; __device__ __forceinline__ float bfhi(unsigned u) { return __uint_as_float(u & 0xffff0000u); }
; __device__ __forceinline__ v4i16 tr16(const unsigned char* p) { return __builtin_amdgcn_ds_read_tr16_b64_v4i16((LDSAS v4i16*)p); }
; __device__ __forceinline__ bf16x8 cat8(v4i16 a, v4i16 b) { return (bf16x8){a[0], a[1], a[2], a[3], b[0], b[1], b[2], b[3]}; }
; __device__ __forceinline__ void st4bf(bf16_t* dst, f32x4 v) { u32x2 pk; pk.x = pk2(v.x, v.y); pk.y = pk2(v.z, v.w); *(u32x2*)dst = pk; }
; template <int PASS>
; __device__ void ssd_item(const Params& p, int item, int l, unsigned char* smem) {
;     ...
;             const unsigned char* xtr = (const unsigned char*)Xs + (8 * kq + (idx >> 2)) * 144 + (16 * w + 4 * (idx & 3)) * 2;
;             const bf16x8 xf = cat8(tr16(xtr), tr16(xtr + 4 * 144));
; #pragma unroll 1
;             for (int it2 = 0; it2 < 2; ++it2) {
;                 const int ii = 16 * it2 + idx;
;                 const bf16x8 gf = *(const bf16x8*)(Gs + ii * 40 + 8 * kq);
;                 f32x4 yd = (f32x4){0.f, 0.f, 0.f, 0.f}, yo = (f32x4){0.f, 0.f, 0.f, 0.f};
;                 bf16x8 sf[4], cf[4];
; #pragma unroll
;                 for (int ks = 0; ks < 4; ++ks) { sf[ks] = *(const bf16x8*)(Sb + (16 * w + idx) * 136 + ks * 32 + kq * 8); cf[ks] = *(const bf16x8*)(Cs + ii * 136 + ks * 32 + kq * 8); }
;                 __builtin_amdgcn_sched_barrier(0);
;                 yd = __builtin_amdgcn_mfma_f32_16x16x32_bf16(xf, gf, yd, 0, 0, 0);
; #pragma unroll
;                 for (int ks = 0; ks < 4; ++ks) yo = __builtin_amdgcn_mfma_f32_16x16x32_bf16(sf[ks], cf[ks], yo, 0, 0, 0);
;                 __builtin_amdgcn_sched_barrier(0);
;                 f32x4 y = yd + yo * s_rs[ii];
;                 if (dir == 0) { const u32x2 xv = *(const u32x2*)(Xs + ii * 72 + 16 * w + 4 * kq);
;                     y.x += Dh * bflo(xv.x); y.y += Dh * bfhi(xv.x); y.z += Dh * bflo(xv.y); y.w += Dh * bfhi(xv.y); }
;                 st4bf(Y + (tokb + t0 + ii) * 512 + h * 64 + 16 * w + 4 * kq, y);
;             }
.LBB0_932:
	v_or_b32_e32 v41, s23, v53
	v_mad_u32_u24 v36, v41, s1, v56
	v_mad_u32_u24 v50, v41, s0, v56
	v_lshl_add_u32 v185, v41, 2, v40
	ds_read_b32 v186, v185 offset:48640
	v_mad_u32_u24 v188, v41, s3, v76
	ds_read_b64 v[188:189], v188 offset:17408
	ds_read_b128 v[36:39], v36 offset:26624
	ds_read_b128 v[42:45], v50 offset:8704
	ds_read_b128 v[46:49], v75 offset:29184
	ds_read_b128 v[96:99], v75 offset:29248
	ds_read_b128 v[100:103], v50 offset:8768
	ds_read_b128 v[104:107], v50 offset:8832
	ds_read_b128 v[108:111], v75 offset:29312
	ds_read_b128 v[112:115], v75 offset:29376
	ds_read_b128 v[116:119], v50 offset:8896
	s_waitcnt lgkmcnt(6)
	v_mfma_f32_16x16x32_bf16 v[42:45], v[46:49], v[42:45], 0
	s_waitcnt lgkmcnt(4)
	v_mfma_f32_16x16x32_bf16 v[42:45], v[96:99], v[100:103], v[42:45]
	s_waitcnt lgkmcnt(2)
	v_mfma_f32_16x16x32_bf16 v[42:45], v[108:111], v[104:107], v[42:45]
	s_waitcnt lgkmcnt(0)
	v_mfma_f32_16x16x32_bf16 v[42:45], v[112:115], v[116:119], v[42:45]
	v_mfma_f32_16x16x32_bf16 v[46:49], v[32:35], v[36:39], 0
	s_nop 1
	s_andn2_b64 vcc, exec, s[36:37]
	s_waitcnt lgkmcnt(0)
	s_nop 3
	v_pk_fma_f32 v[36:37], v[44:45], v[186:187], v[48:49] op_sel_hi:[1,0,1]
	v_pk_fma_f32 v[38:39], v[42:43], v[186:187], v[46:47] op_sel_hi:[1,0,1]
	s_cbranch_vccnz .LBB0_931
	v_lshlrev_b32_e32 v44, 16, v188
	v_and_b32_e32 v45, 0xffff0000, v188
	v_lshlrev_b32_e32 v42, 16, v189
	v_and_b32_e32 v43, 0xffff0000, v189
	v_pk_fma_f32 v[38:39], v[54:55], v[44:45], v[38:39]
	v_pk_fma_f32 v[36:37], v[54:55], v[42:43], v[36:37]
	s_branch .LBB0_931
.LBB0_963:
	v_sub_f32_e32 v38, v37, v174
	v_mul_f32_e32 v38, 0x3fb8aa3b, v38
	v_exp_f32_e32 v38, v38
	s_nop 0
	v_mul_f32_e32 v38, v175, v38
	v_mul_f32_e32 v38, v32, v38
	s_or_b64 exec, exec, s[66:67]
	v_mov_b32_e32 v32, 0
	s_and_saveexec_b64 s[66:67], s[60:61]
	s_cbranch_execz .LBB0_927
